# attn v1 + scan loop vmcnt(0) moved off the chunk-loop top to before the H stores
# baseline (speedup 1.0000x reference)
; #define LDS_BARRIER() asm volatile("s_waitcnt lgkmcnt(0)\n\ts_barrier" ::: "memory")
; #define XR_LOAD(ckv) do { const int tb_ = 128 * (ckv) + 16 * wid - 2; _Pragma("unroll") for (int i = 0; i < 3; ++i) { const int idx = lane + 64 * i, r = idx >> 3, c8 = idx & 7, t = tb_ + r; \
;         xw[i] = (u32x4){0u, 0u, 0u, 0u}; if (idx < 152 && t >= 0 && t < TT) xw[i] = *(const u32x4*)(P + ((size_t)b * TT + t) * INP + C_XR + 64 * g + 8 * c8); } } while (0)
; template <int DIR>
; __device__ __forceinline__ void rnn_scan_unit(const Params& p, LAS unsigned char* lds, int b, int g) {
;     ...
;     const int ch = lane, seg = wid;
;     LDS_BARRIER();
;     bf16x8 wreg[8];
; #pragma unroll
;     for (int f = 0; f < 8; ++f) wreg[f] = wl[f * 64 + lane];
;     f32x4 cwv[4][2], cbv[2];
;     { const int c0 = 64 * g + 8 * (lane & 7);
; #pragma unroll
;       for (int j = 0; j < 4; ++j) { cwv[j][0] = *(const f32x4*)(p.in[10] + j * 512 + c0); cwv[j][1] = *(const f32x4*)(p.in[10] + j * 512 + c0 + 4); }
;       cbv[0] = *(const f32x4*)(p.in[11] + c0); cbv[1] = *(const f32x4*)(p.in[11] + c0 + 4); }
;     float hcar = 0.f;
;     u32x4 xw[3];
;     ...
;     XR_LOAD(DIR == 0 ? 0 : NCH - 1);
; #pragma unroll 1
;     for (int ci = 0; ci < NCH; ++ci) {
;         const int ck = DIR == 0 ? ci : NCH - 1 - ci, t0 = 128 * ck + 16 * wid;
.LBB0_538:
	s_or_b64 exec, exec, s[0:1]
	s_movk_i32 s0, 0x3a80
	v_mul_lo_u32 v0, v89, s0
	v_bfe_u32 v91, v116, 4, 2
	v_add_u32_e32 v98, 0, v0
	s_movk_i32 s0, 0x110
	v_mad_u32_u24 v100, v92, s0, v98
	v_lshlrev_b32_e32 v101, 5, v91
	v_lshlrev_b32_e32 v91, 4, v91
	v_lshlrev_b32_e32 v102, 4, v92
	v_add_u32_e32 v128, v100, v91
	s_add_i32 s0, 0, 0x23400
	v_sub_u32_e32 v130, v128, v102
	v_or_b32_e32 v102, 64, v91
	v_add_u32_e32 v126, s0, v91
	v_add_u32_e32 v127, s33, v91
	v_add_u32_e32 v129, s79, v91
	v_add_u32_e32 v131, s0, v102
	v_add_u32_e32 v132, s33, v102
	v_add_u32_e32 v133, s79, v102
	v_or_b32_e32 v102, 0x80, v91
	v_or_b32_e32 v91, 0xc0, v91
	s_lshl_b32 s17, s34, 1
	v_add_u32_e32 v137, s0, v91
	v_add_u32_e32 v138, s33, v91
	v_add_u32_e32 v139, s79, v91
	v_lshl_or_b32 v91, v116, 2, v152
	s_add_u32 s68, s40, s17
	v_add_u32_e32 v123, v98, v90
	v_lshrrev_b32_e32 v0, 2, v122
	v_add_u32_e32 v134, s0, v102
	v_add_u32_e32 v155, v98, v91
	v_cmp_eq_u32_e64 s[0:1], 6, v89
	v_cmp_eq_u32_e64 s[2:3], 5, v89
	v_cmp_eq_u32_e64 s[4:5], 4, v89
	v_cmp_eq_u32_e64 s[8:9], 3, v89
	v_cmp_eq_u32_e64 s[10:11], 2, v89
	v_cmp_eq_u32_e64 s[12:13], 1, v89
	s_addc_u32 s69, s41, 0
	v_mov_b32_e32 v91, v1
	v_ashrrev_i32_e32 v89, 31, v88
	v_add_u32_e32 v99, v123, v90
	v_lshl_add_u64 v[118:119], s[68:69], 0, v[90:91]
	v_lshl_add_u64 v[90:91], v[0:1], 0, v[88:89]
	v_lshlrev_b64 v[90:91], 10, v[90:91]
	v_mad_i64_i32 v[90:91], s[16:17], s16, v153, v[90:91]
	v_lshlrev_b32_e32 v104, 6, v116
	v_add3_u32 v156, v3, v88, s95
	s_lshl_b32 s16, s72, 6
	v_and_b32_e32 v3, 3, v116
	v_lshlrev_b32_e32 v103, 8, v0
	v_and_b32_e32 v104, 0xc0, v104
	v_lshlrev_b32_e32 v125, 7, v94
	s_and_b32 s16, s16, 0x380
	v_lshlrev_b32_e32 v3, 5, v3
	v_add3_u32 v124, v98, v103, v104
	v_lshlrev_b32_e32 v96, 4, v96
	v_lshlrev_b32_e32 v97, 4, v97
	v_mul_u32_u24_e32 v103, 0x110, v94
	v_or_b32_e32 v104, 0x400, v125
	v_or3_b32 v90, v90, s16, v3
	s_movk_i32 s6, 0x800
	v_add_u32_e32 v135, s33, v102
	v_add_u32_e32 v136, s79, v102
	v_lshl_add_u32 v154, v122, 2, v98
	v_cmp_gt_u32_e64 s[14:15], 64, v116
	v_add3_u32 v157, v95, v88, s95
	v_add3_u32 v158, v94, v88, s95
	v_lshl_add_u64 v[120:121], s[96:97], 0, v[90:91]
	v_add3_u32 v159, v0, v88, s6
	v_add3_u32 v160, v88, v92, s6
	s_mov_b32 s19, 0
	v_add_u32_e32 v161, v98, v93
	v_add_u32_e32 v164, v98, v96
	v_add_u32_e32 v165, v98, v97
	v_add_u32_e32 v166, v99, v103
	v_add_u32_e32 v167, v123, v104
	v_add_u32_e32 v168, v100, v101
	s_mov_b32 s34, 0
	s_waitcnt vmcnt(0)
	s_branch .LBB0_540

; #define LAS __attribute__((address_space(3)))
; #define XR_LOAD(ckv) do { const int tb_ = 128 * (ckv) + 16 * wid - 2; _Pragma("unroll") for (int i = 0; i < 3; ++i) { const int idx = lane + 64 * i, r = idx >> 3, c8 = idx & 7, t = tb_ + r; \
;         xw[i] = (u32x4){0u, 0u, 0u, 0u}; if (idx < 152 && t >= 0 && t < TT) xw[i] = *(const u32x4*)(P + ((size_t)b * TT + t) * INP + C_XR + 64 * g + 8 * c8); } } while (0)
; template <int DIR>
; __device__ __forceinline__ void rnn_scan_unit(const Params& p, LAS unsigned char* lds, int b, int g) {
;     ...
;         const int ck = DIR == 0 ? ci : NCH - 1 - ci, t0 = 128 * ck + 16 * wid;
; #pragma unroll
;         for (int i = 0; i < 3; ++i) { const int idx = lane + 64 * i; if (idx < 152) *(LAS u32x4*)(xrb + idx * 8) = xw[i]; }
;         asm volatile("s_waitcnt lgkmcnt(0)" ::: "memory");
;         if (ci + 1 < NCH) XR_LOAD(DIR == 0 ? ci + 1 : NCH - 2 - ci);
.LBB0_540:
	ds_write_b128 v161, v[76:79]
	ds_write_b128 v164, v[80:83]
	s_and_saveexec_b64 s[16:17], vcc
	ds_write_b128 v165, v[84:87]
	s_or_b64 exec, exec, s[16:17]
	s_waitcnt lgkmcnt(0)
	s_cmpk_eq_i32 s19, 0xf800
	s_cbranch_scc1 .LBB0_550
	v_mov_b32_e32 v80, v1
	v_mov_b32_e32 v81, v1
	v_add_u32_e32 v0, s19, v158
	v_mov_b32_e32 v82, v1
	v_mov_b32_e32 v83, v1
	v_mov_b64_e32 v[76:77], v[80:81]
	v_cmp_gt_u32_e64 s[16:17], s86, v0
	v_mov_b64_e32 v[78:79], v[82:83]
	s_and_saveexec_b64 s[76:77], s[16:17]
	s_cbranch_execz .LBB0_545
	v_lshl_add_u64 v[76:77], s[74:75], 0, v[0:1]
	v_mad_u64_u32 v[78:79], s[16:17], v76, s89, v[118:119]
	v_mov_b32_e32 v0, v79
	v_mad_u64_u32 v[76:77], s[16:17], v77, s89, v[0:1]
	v_mov_b32_e32 v79, v76
	global_load_dwordx4 v[76:79], v[78:79], off offset:1344

; #define LAS __attribute__((address_space(3)))
; __device__ __forceinline__ unsigned cvt_pk(float lo, float hi) { unsigned r; asm("v_cvt_pk_bf16_f32 %0, %1, %2" : "=v"(r) : "v"(lo), "v"(hi)); return r; }
; #define LDS_BARRIER() asm volatile("s_waitcnt lgkmcnt(0)\n\ts_barrier" ::: "memory")
; template <int DIR>
; __device__ __forceinline__ void rnn_scan_unit(const Params& p, LAS unsigned char* lds, int b, int g) {
;     ...
;               *(LAS f32x4*)(al + tt * 64 + c4) = av; *(LAS f32x4*)(bl + tt * 64 + c4) = bv; } }
;         asm volatile("s_waitcnt lgkmcnt(0)" ::: "memory");
;         LAS float* sgA = sg + (ci & 1) * 1024; LAS float* sgB = sgA + 512;
;         float av_[16], bv_[16];
;         { float A = 1.f, B = 0.f;
; #pragma unroll
;           for (int k = 0; k < 16; ++k) { const int tt = DIR == 0 ? k : 15 - k; av_[k] = al[tt * 64 + ch]; bv_[k] = bl[tt * 64 + ch]; B = av_[k] * B + bv_[k]; A *= av_[k]; }
;           sgA[seg * 64 + ch] = A; sgB[seg * 64 + ch] = B; }
;         LDS_BARRIER();
;         float h = hcar, hin = hcar;
; #pragma unroll
;         for (int s = 0; s < 8; ++s) { const int sx = DIR == 0 ? s : 7 - s; hin = (sx == seg) ? h : hin; h = sgA[sx * 64 + ch] * h + sgB[sx * 64 + ch]; }
;         hcar = h;
; #pragma unroll
;         for (int k = 0; k < 16; ++k) { const int tt = DIR == 0 ? k : 15 - k; hin = av_[k] * hin + bv_[k]; bl[tt * 64 + ch] = hin; }
;         asm volatile("s_waitcnt lgkmcnt(0)" ::: "memory");
;         { const int tk = lane >> 2, cq4 = lane & 3;
;           if (t0 + tk < TT) { const LAS float* src = bl + tk * 64 + 16 * cq4;
;               const f32x4 x0 = *(const LAS f32x4*)(src), x1 = *(const LAS f32x4*)(src + 4), x2 = *(const LAS f32x4*)(src + 8), x3 = *(const LAS f32x4*)(src + 12);
;               u32x4 w0, w1; w0.x = cvt_pk(x0[0], x0[1]); w0.y = cvt_pk(x0[2], x0[3]); w0.z = cvt_pk(x1[0], x1[1]); w0.w = cvt_pk(x1[2], x1[3]);
;               w1.x = cvt_pk(x2[0], x2[1]); w1.y = cvt_pk(x2[2], x2[3]); w1.z = cvt_pk(x3[0], x3[1]); w1.w = cvt_pk(x3[2], x3[3]);
;               bf16_t* hp = H + ((size_t)b * TT + t0 + tk) * 512 + 64 * g + 16 * cq4;
;               *(u32x4*)hp = w0; *(u32x4*)(hp + 8) = w1; } }
;         asm volatile("s_waitcnt lgkmcnt(0)" ::: "memory");
.LBB0_582:
	s_or_b64 exec, exec, s[76:77]
	v_cndmask_b32_e64 v90, 1.0, v0, s[16:17]
	v_cndmask_b32_e64 v91, 1.0, v3, s[16:17]
	v_cndmask_b32_e64 v92, 1.0, v88, s[16:17]
	v_cndmask_b32_e64 v93, 1.0, v89, s[16:17]
	ds_write_b128 v130, v[90:93] offset:6976
	ds_write_b128 v130, v[104:107] offset:11072
	s_waitcnt lgkmcnt(0)
	v_add_u32_e32 v169, 0x80, v154
	ds_read2st64_b32 v[88:89], v169 offset0:41 offset1:42
	ds_read2st64_b32 v[90:91], v169 offset0:55 offset1:57
	v_add_u32_e32 v3, 0x80, v155
	ds_read2st64_b32 v[92:93], v3 offset0:41 offset1:57
	ds_read2st64_b32 v[94:95], v169 offset0:38 offset1:39
	ds_read2st64_b32 v[172:173], v169 offset0:43 offset1:44
	ds_read2st64_b32 v[98:99], v169 offset0:36 offset1:37
	ds_read2st64_b32 v[102:103], v169 offset0:34 offset1:35
	ds_read2st64_b32 v[96:97], v169 offset0:53 offset1:54
	s_waitcnt lgkmcnt(6)
	v_fma_f32 v0, 0, v88, v91
	ds_read2st64_b32 v[100:101], v169 offset0:51 offset1:52
	ds_read2st64_b32 v[104:105], v169 offset0:49 offset1:50
	ds_read2st64_b32 v[108:109], v169 offset0:47 offset1:48
	ds_read2st64_b32 v[114:115], v169 offset0:45 offset1:46
	s_waitcnt lgkmcnt(9)
	v_fma_f32 v0, v0, v92, v93
	v_mul_f32_e32 v3, v88, v92
	s_waitcnt lgkmcnt(8)
	v_fma_f32 v0, v0, v95, v90
	v_mul_f32_e32 v3, v3, v95
	s_waitcnt lgkmcnt(4)
	v_fma_f32 v0, v0, v94, v97
	v_mul_f32_e32 v3, v3, v94
	ds_read2st64_b32 v[106:107], v169 offset0:32 offset1:33
	ds_read2st64_b32 v[112:113], v169 offset0:30 offset1:31
	ds_read2st64_b32 v[170:171], v169 offset0:28 offset1:29
	ds_read2st64_b32 v[174:175], v169 offset0:26 offset1:27
	v_fma_f32 v0, v0, v99, v96
	v_mul_f32_e32 v3, v3, v99
	s_waitcnt lgkmcnt(7)
	v_fma_f32 v0, v0, v98, v101
	v_mul_f32_e32 v3, v3, v98
	v_fma_f32 v0, v0, v103, v100
	v_mul_f32_e32 v3, v3, v103
	s_waitcnt lgkmcnt(6)
	v_fma_f32 v0, v0, v102, v105
	v_mul_f32_e32 v3, v3, v102
	s_waitcnt lgkmcnt(3)
	v_fma_f32 v0, v0, v107, v104
	v_mul_f32_e32 v3, v3, v107
	v_fma_f32 v0, v0, v106, v109
	v_mul_f32_e32 v3, v3, v106
	s_waitcnt lgkmcnt(2)
	v_fma_f32 v0, v0, v113, v108
	v_mul_f32_e32 v3, v3, v113
	s_and_b32 s16, s34, 0x400
	v_fma_f32 v0, v0, v112, v115
	v_mul_f32_e32 v3, v3, v112
	s_lshl_b32 s16, s16, 2
	s_waitcnt lgkmcnt(1)
	v_fma_f32 v0, v0, v171, v114
	v_mul_f32_e32 v3, v3, v171
	s_add_i32 s16, s16, 0
	v_fma_f32 v0, v0, v170, v173
	v_mul_f32_e32 v3, v3, v170
	s_add_i32 s16, s16, 0x1d400
	s_waitcnt lgkmcnt(0)
	v_fma_f32 v0, v0, v175, v172
	v_mul_f32_e32 v3, v3, v175
	v_fma_f32 v0, v0, v174, v89
	v_mul_f32_e32 v3, v3, v174
	v_lshl_add_u32 v110, v116, 2, s16
	ds_write2st64_b32 v110, v3, v0 offset1:8
	s_waitcnt lgkmcnt(0)
	s_barrier
	v_lshl_add_u32 v0, v122, 2, s16
	ds_read2st64_b32 v[110:111], v0 offset0:6 offset1:7
	ds_read2st64_b32 v[176:177], v0 offset0:14 offset1:15
	s_waitcnt lgkmcnt(0)
	v_fma_f32 v3, v2, v111, v177
	v_cndmask_b32_e64 v2, v2, v3, s[0:1]
	v_fmac_f32_e32 v176, v3, v110
	v_cndmask_b32_e64 v177, v2, v176, s[2:3]
	ds_read2st64_b32 v[2:3], v0 offset0:4 offset1:5
	ds_read2st64_b32 v[110:111], v0 offset0:12 offset1:13
	s_waitcnt lgkmcnt(0)
	v_fma_f32 v3, v176, v3, v111
	v_cndmask_b32_e64 v111, v177, v3, s[4:5]
	v_fmac_f32_e32 v110, v3, v2
	ds_read2st64_b32 v[2:3], v0 offset0:2 offset1:3
	ds_read2st64_b32 v[176:177], v0 offset0:10 offset1:11
	v_cndmask_b32_e64 v111, v111, v110, s[8:9]
	s_waitcnt lgkmcnt(0)
	v_fma_f32 v3, v110, v3, v177
	v_cndmask_b32_e64 v110, v111, v3, s[10:11]
	v_fmac_f32_e32 v176, v3, v2
	v_cndmask_b32_e64 v177, v110, v176, s[12:13]
	ds_read2st64_b32 v[110:111], v0 offset1:1
	ds_read2st64_b32 v[2:3], v0 offset0:8 offset1:9
	s_waitcnt lgkmcnt(0)
	v_fma_f32 v0, v176, v111, v3
	v_cndmask_b32_e64 v3, v177, v0, s[14:15]
	v_fma_f32 v3, v88, v3, v91
	v_fmac_f32_e32 v93, v92, v3
	v_fmac_f32_e32 v90, v95, v93
	ds_write_b32 v154, v3 offset:14720
	v_fma_f32 v3, v94, v90, v97
	v_fmac_f32_e32 v96, v99, v3
	ds_write2st64_b32 v169, v3, v90 offset0:54 offset1:55
	v_fma_f32 v3, v98, v96, v101
	v_fmac_f32_e32 v100, v103, v3
	ds_write2st64_b32 v169, v3, v96 offset0:52 offset1:53
	v_fma_f32 v3, v102, v100, v105
	v_fmac_f32_e32 v104, v107, v3
	ds_write2st64_b32 v169, v3, v100 offset0:50 offset1:51
	v_fma_f32 v3, v106, v104, v109
	v_fmac_f32_e32 v108, v113, v3
	ds_write2st64_b32 v169, v3, v104 offset0:48 offset1:49
	v_fma_f32 v3, v112, v108, v115
	v_fmac_f32_e32 v114, v171, v3
	ds_write2st64_b32 v169, v3, v108 offset0:46 offset1:47
	v_fma_f32 v3, v170, v114, v173
	v_fmac_f32_e32 v172, v175, v3
	v_fmac_f32_e32 v89, v174, v172
	ds_write_b32 v155, v93 offset:14720
	ds_write2st64_b32 v169, v3, v114 offset0:44 offset1:45
	ds_write2st64_b32 v169, v89, v172 offset0:42 offset1:43
	s_waitcnt lgkmcnt(0)
	v_add_u32_e32 v3, s19, v159
	v_cmp_gt_i32_e64 s[16:17], s86, v3
	s_waitcnt vmcnt(0)
	s_and_saveexec_b64 s[76:77], s[16:17]
	s_cbranch_execz .LBB0_539
	ds_read_b128 v[88:91], v124 offset:10880
	ds_read_b128 v[92:95], v124 offset:10896
	ds_read_b128 v[96:99], v124 offset:10912
	ds_read_b128 v[100:103], v124 offset:10928
	s_waitcnt lgkmcnt(3)
	v_cvt_pk_bf16_f32 v88, v88, v89
	v_cvt_pk_bf16_f32 v89, v90, v91
	s_waitcnt lgkmcnt(2)
	v_cvt_pk_bf16_f32 v90, v92, v93
	v_cvt_pk_bf16_f32 v91, v94, v95
	s_waitcnt lgkmcnt(1)
	v_cvt_pk_bf16_f32 v92, v96, v97
	v_cvt_pk_bf16_f32 v93, v98, v99
	s_waitcnt lgkmcnt(0)
	v_cvt_pk_bf16_f32 v94, v100, v101
	v_cvt_pk_bf16_f32 v95, v102, v103
	global_store_dwordx4 v[120:121], v[88:91], off
	global_store_dwordx4 v[120:121], v[92:95], off offset:16
	s_branch .LBB0_539

; #define LDS_BARRIER() asm volatile("s_waitcnt lgkmcnt(0)\n\ts_barrier" ::: "memory")
; #define XR_LOAD(ckv) do { const int tb_ = 128 * (ckv) + 16 * wid - 2; _Pragma("unroll") for (int i = 0; i < 3; ++i) { const int idx = lane + 64 * i, r = idx >> 3, c8 = idx & 7, t = tb_ + r; \
;         xw[i] = (u32x4){0u, 0u, 0u, 0u}; if (idx < 152 && t >= 0 && t < TT) xw[i] = *(const u32x4*)(P + ((size_t)b * TT + t) * INP + C_XR + 64 * g + 8 * c8); } } while (0)
; template <int DIR>
; __device__ __forceinline__ void rnn_scan_unit(const Params& p, LAS unsigned char* lds, int b, int g) {
;     ...
;     const int ch = lane, seg = wid;
;     LDS_BARRIER();
;     bf16x8 wreg[8];
; #pragma unroll
;     for (int f = 0; f < 8; ++f) wreg[f] = wl[f * 64 + lane];
;     f32x4 cwv[4][2], cbv[2];
;     { const int c0 = 64 * g + 8 * (lane & 7);
; #pragma unroll
;       for (int j = 0; j < 4; ++j) { cwv[j][0] = *(const f32x4*)(p.in[10] + j * 512 + c0); cwv[j][1] = *(const f32x4*)(p.in[10] + j * 512 + c0 + 4); }
;       cbv[0] = *(const f32x4*)(p.in[11] + c0); cbv[1] = *(const f32x4*)(p.in[11] + c0 + 4); }
;     float hcar = 0.f;
;     u32x4 xw[3];
;     ...
;     XR_LOAD(DIR == 0 ? 0 : NCH - 1);
; #pragma unroll 1
;     for (int ci = 0; ci < NCH; ++ci) {
;         const int ck = DIR == 0 ? ci : NCH - 1 - ci, t0 = 128 * ck + 16 * wid;
.LBB0_594:
	s_or_b64 exec, exec, s[0:1]
	s_movk_i32 s0, 0x3a80
	v_mul_lo_u32 v0, v89, s0
	v_bfe_u32 v91, v120, 4, 2
	v_add_u32_e32 v98, 0, v0
	s_movk_i32 s0, 0x110
	v_mad_u32_u24 v100, v92, s0, v98
	v_lshlrev_b32_e32 v101, 5, v91
	v_lshlrev_b32_e32 v91, 4, v91
	v_lshlrev_b32_e32 v102, 4, v92
	v_add_u32_e32 v129, v100, v91
	s_add_i32 s0, 0, 0x23400
	v_sub_u32_e32 v131, v129, v102
	v_or_b32_e32 v102, 64, v91
	s_lshl_b32 s16, s16, 1
	v_add_u32_e32 v127, s0, v91
	v_add_u32_e32 v128, s33, v91
	v_add_u32_e32 v130, s79, v91
	v_add_u32_e32 v132, s0, v102
	v_add_u32_e32 v133, s33, v102
	v_add_u32_e32 v134, s79, v102
	v_or_b32_e32 v102, 0x80, v91
	v_or_b32_e32 v91, 0xc0, v91
	s_add_u32 s16, s40, s16
	v_add_u32_e32 v123, v98, v90
	v_lshrrev_b32_e32 v0, 2, v121
	v_add_u32_e32 v138, s0, v91
	v_add_u32_e32 v139, s33, v91
	v_add_u32_e32 v154, s79, v91
	s_addc_u32 s17, s41, 0
	v_mov_b32_e32 v91, v1
	v_add_u32_e32 v99, v123, v90
	v_add_u32_e32 v135, s0, v102
	v_cmp_eq_u32_e64 s[0:1], 1, v89
	v_cmp_eq_u32_e64 s[2:3], 2, v89
	v_cmp_eq_u32_e64 s[4:5], 3, v89
	v_cmp_eq_u32_e64 s[8:9], 4, v89
	v_cmp_eq_u32_e64 s[10:11], 5, v89
	v_cmp_eq_u32_e64 s[12:13], 6, v89
	v_cmp_eq_u32_e64 s[14:15], 7, v89
	v_lshl_add_u64 v[116:117], s[16:17], 0, v[90:91]
	v_lshl_add_u64 v[90:91], v[0:1], 0, s[74:75]
	v_ashrrev_i32_e32 v89, 31, v88
	v_lshlrev_b32_e32 v104, 6, v120
	v_add3_u32 v155, v2, v88, s70
	v_lshl_add_u64 v[90:91], v[90:91], 0, v[88:89]
	s_lshl_b32 s16, s72, 6
	v_and_b32_e32 v2, 3, v120
	v_lshlrev_b32_e32 v103, 8, v0
	v_and_b32_e32 v104, 0xc0, v104
	v_lshlrev_b32_e32 v126, 7, v94
	v_lshlrev_b64 v[90:91], 10, v[90:91]
	s_and_b32 s16, s16, 0x380
	v_lshlrev_b32_e32 v2, 5, v2
	v_add3_u32 v125, v98, v103, v104
	v_lshlrev_b32_e32 v96, 4, v96
	v_lshlrev_b32_e32 v97, 4, v97
	v_mul_u32_u24_e32 v103, 0x110, v94
	v_or_b32_e32 v104, 0x400, v126
	v_or3_b32 v90, v90, s16, v2
	v_lshl_add_u32 v124, v121, 2, v98
	v_add_u32_e32 v136, s33, v102
	v_add_u32_e32 v137, s79, v102
	v_add3_u32 v156, v95, v88, s70
	v_add3_u32 v157, v94, v88, s70
	v_lshl_add_u64 v[118:119], s[80:81], 0, v[90:91]
	v_add_u32_e32 v158, v0, v88
	v_add_u32_e32 v159, v88, v92
	s_mov_b32 s19, 0
	v_add_u32_e32 v160, v98, v93
	v_add_u32_e32 v161, v98, v96
	v_add_u32_e32 v164, v98, v97
	v_add_u32_e32 v165, v99, v103
	v_add_u32_e32 v166, v123, v104
	v_add_u32_e32 v167, v100, v101
	s_mov_b32 s34, 0
	s_waitcnt vmcnt(0)
	s_branch .LBB0_596

; #define LAS __attribute__((address_space(3)))
; #define XR_LOAD(ckv) do { const int tb_ = 128 * (ckv) + 16 * wid - 2; _Pragma("unroll") for (int i = 0; i < 3; ++i) { const int idx = lane + 64 * i, r = idx >> 3, c8 = idx & 7, t = tb_ + r; \
;         xw[i] = (u32x4){0u, 0u, 0u, 0u}; if (idx < 152 && t >= 0 && t < TT) xw[i] = *(const u32x4*)(P + ((size_t)b * TT + t) * INP + C_XR + 64 * g + 8 * c8); } } while (0)
; template <int DIR>
; __device__ __forceinline__ void rnn_scan_unit(const Params& p, LAS unsigned char* lds, int b, int g) {
;     ...
;         const int ck = DIR == 0 ? ci : NCH - 1 - ci, t0 = 128 * ck + 16 * wid;
; #pragma unroll
;         for (int i = 0; i < 3; ++i) { const int idx = lane + 64 * i; if (idx < 152) *(LAS u32x4*)(xrb + idx * 8) = xw[i]; }
;         asm volatile("s_waitcnt lgkmcnt(0)" ::: "memory");
;         if (ci + 1 < NCH) XR_LOAD(DIR == 0 ? ci + 1 : NCH - 2 - ci);
.LBB0_596:
	ds_write_b128 v160, v[76:79]
	ds_write_b128 v161, v[80:83]
	s_and_saveexec_b64 s[16:17], vcc
	ds_write_b128 v164, v[84:87]
	s_or_b64 exec, exec, s[16:17]
	s_waitcnt lgkmcnt(0)
	s_cmpk_eq_i32 s19, 0x800
	s_cbranch_scc1 .LBB0_606
	v_mov_b32_e32 v80, v1
	v_mov_b32_e32 v81, v1
	v_add_u32_e32 v0, s19, v157
	v_mov_b32_e32 v82, v1
	v_mov_b32_e32 v83, v1
	v_mov_b64_e32 v[76:77], v[80:81]
	v_cmp_gt_u32_e64 s[16:17], s86, v0
	v_mov_b64_e32 v[78:79], v[82:83]
	s_and_saveexec_b64 s[76:77], s[16:17]
	s_cbranch_execz .LBB0_601
	v_lshl_add_u64 v[76:77], s[74:75], 0, v[0:1]
	v_mad_u64_u32 v[78:79], s[16:17], v76, s89, v[116:117]
	v_mov_b32_e32 v0, v79
	v_mad_u64_u32 v[76:77], s[16:17], v77, s89, v[0:1]
	v_mov_b32_e32 v79, v76
	global_load_dwordx4 v[76:79], v[78:79], off offset:1344

; #define LAS __attribute__((address_space(3)))
; __device__ __forceinline__ unsigned cvt_pk(float lo, float hi) { unsigned r; asm("v_cvt_pk_bf16_f32 %0, %1, %2" : "=v"(r) : "v"(lo), "v"(hi)); return r; }
; #define LDS_BARRIER() asm volatile("s_waitcnt lgkmcnt(0)\n\ts_barrier" ::: "memory")
; template <int DIR>
; __device__ __forceinline__ void rnn_scan_unit(const Params& p, LAS unsigned char* lds, int b, int g) {
;     ...
;               *(LAS f32x4*)(al + tt * 64 + c4) = av; *(LAS f32x4*)(bl + tt * 64 + c4) = bv; } }
;         asm volatile("s_waitcnt lgkmcnt(0)" ::: "memory");
;         LAS float* sgA = sg + (ci & 1) * 1024; LAS float* sgB = sgA + 512;
;         float av_[16], bv_[16];
;         { float A = 1.f, B = 0.f;
; #pragma unroll
;           for (int k = 0; k < 16; ++k) { const int tt = DIR == 0 ? k : 15 - k; av_[k] = al[tt * 64 + ch]; bv_[k] = bl[tt * 64 + ch]; B = av_[k] * B + bv_[k]; A *= av_[k]; }
;           sgA[seg * 64 + ch] = A; sgB[seg * 64 + ch] = B; }
;         LDS_BARRIER();
;         float h = hcar, hin = hcar;
; #pragma unroll
;         for (int s = 0; s < 8; ++s) { const int sx = DIR == 0 ? s : 7 - s; hin = (sx == seg) ? h : hin; h = sgA[sx * 64 + ch] * h + sgB[sx * 64 + ch]; }
;         hcar = h;
; #pragma unroll
;         for (int k = 0; k < 16; ++k) { const int tt = DIR == 0 ? k : 15 - k; hin = av_[k] * hin + bv_[k]; bl[tt * 64 + ch] = hin; }
;         asm volatile("s_waitcnt lgkmcnt(0)" ::: "memory");
;         { const int tk = lane >> 2, cq4 = lane & 3;
;           if (t0 + tk < TT) { const LAS float* src = bl + tk * 64 + 16 * cq4;
;               const f32x4 x0 = *(const LAS f32x4*)(src), x1 = *(const LAS f32x4*)(src + 4), x2 = *(const LAS f32x4*)(src + 8), x3 = *(const LAS f32x4*)(src + 12);
;               u32x4 w0, w1; w0.x = cvt_pk(x0[0], x0[1]); w0.y = cvt_pk(x0[2], x0[3]); w0.z = cvt_pk(x1[0], x1[1]); w0.w = cvt_pk(x1[2], x1[3]);
;               w1.x = cvt_pk(x2[0], x2[1]); w1.y = cvt_pk(x2[2], x2[3]); w1.z = cvt_pk(x3[0], x3[1]); w1.w = cvt_pk(x3[2], x3[3]);
;               bf16_t* hp = H + ((size_t)b * TT + t0 + tk) * 512 + 64 * g + 16 * cq4;
;               *(u32x4*)hp = w0; *(u32x4*)(hp + 8) = w1; } }
;         asm volatile("s_waitcnt lgkmcnt(0)" ::: "memory");
.LBB0_638:
	s_or_b64 exec, exec, s[76:77]
	v_cndmask_b32_e64 v90, 1.0, v0, s[16:17]
	v_cndmask_b32_e64 v91, 1.0, v2, s[16:17]
	v_cndmask_b32_e64 v92, 1.0, v88, s[16:17]
	v_cndmask_b32_e64 v93, 1.0, v89, s[16:17]
	ds_write_b128 v131, v[90:93] offset:6976
	ds_write_b128 v131, v[104:107] offset:11072
	s_waitcnt lgkmcnt(0)
	v_add_u32_e32 v176, 0x80, v124
	ds_read2st64_b32 v[88:89], v176 offset0:26 offset1:27
	ds_read2st64_b32 v[90:91], v176 offset0:42 offset1:43
	ds_read2st64_b32 v[94:95], v176 offset0:28 offset1:29
	ds_read2st64_b32 v[92:93], v176 offset0:44 offset1:45
	ds_read2st64_b32 v[98:99], v176 offset0:30 offset1:31
	ds_read2st64_b32 v[96:97], v176 offset0:46 offset1:47
	ds_read2st64_b32 v[100:101], v176 offset0:32 offset1:33
	ds_read2st64_b32 v[102:103], v176 offset0:48 offset1:49
	s_waitcnt lgkmcnt(7)
	v_mul_f32_e32 v2, v88, v89
	s_waitcnt lgkmcnt(6)
	v_fma_f32 v0, 0, v88, v90
	v_fma_f32 v0, v0, v89, v91
	s_waitcnt lgkmcnt(4)
	v_fma_f32 v0, v0, v94, v92
	v_mul_f32_e32 v2, v2, v94
	v_fma_f32 v0, v0, v95, v93
	v_mul_f32_e32 v2, v2, v95
	ds_read2st64_b32 v[104:105], v176 offset0:34 offset1:35
	ds_read2st64_b32 v[106:107], v176 offset0:50 offset1:51
	s_waitcnt lgkmcnt(4)
	v_fma_f32 v0, v0, v98, v96
	v_mul_f32_e32 v2, v2, v98
	v_fma_f32 v0, v0, v99, v97
	v_mul_f32_e32 v2, v2, v99
	ds_read2st64_b32 v[110:111], v176 offset0:36 offset1:37
	ds_read2st64_b32 v[108:109], v176 offset0:52 offset1:53
	s_waitcnt lgkmcnt(4)
	v_fma_f32 v0, v0, v100, v102
	v_mul_f32_e32 v2, v2, v100
	v_fma_f32 v0, v0, v101, v103
	v_mul_f32_e32 v2, v2, v101
	ds_read2st64_b32 v[114:115], v176 offset0:38 offset1:39
	ds_read2st64_b32 v[168:169], v176 offset0:54 offset1:55
	s_waitcnt lgkmcnt(4)
	v_fma_f32 v0, v0, v104, v106
	v_mul_f32_e32 v2, v2, v104
	v_fma_f32 v0, v0, v105, v107
	v_mul_f32_e32 v2, v2, v105
	ds_read2st64_b32 v[170:171], v176 offset0:40 offset1:41
	ds_read2st64_b32 v[172:173], v176 offset0:56 offset1:57
	s_waitcnt lgkmcnt(4)
	v_fma_f32 v0, v0, v110, v108
	v_mul_f32_e32 v2, v2, v110
	s_and_b32 s16, s34, 0x400
	v_fma_f32 v0, v0, v111, v109
	v_mul_f32_e32 v2, v2, v111
	s_lshl_b32 s16, s16, 2
	s_waitcnt lgkmcnt(2)
	v_fma_f32 v0, v0, v114, v168
	v_mul_f32_e32 v2, v2, v114
	s_add_i32 s16, s16, 0
	v_fma_f32 v0, v0, v115, v169
	v_mul_f32_e32 v2, v2, v115
	s_add_i32 s16, s16, 0x1d400
	s_waitcnt lgkmcnt(0)
	v_fma_f32 v0, v0, v170, v172
	v_mul_f32_e32 v2, v2, v170
	v_fma_f32 v0, v0, v171, v173
	v_mul_f32_e32 v2, v2, v171
	v_lshl_add_u32 v112, v120, 2, s16
	ds_write2st64_b32 v112, v2, v0 offset1:8
	s_waitcnt lgkmcnt(0)
	s_barrier
	v_lshl_add_u32 v0, v121, 2, s16
	ds_read2st64_b32 v[112:113], v0 offset1:1
	ds_read2st64_b32 v[174:175], v0 offset0:8 offset1:9
	s_waitcnt lgkmcnt(0)
	v_fma_f32 v2, v3, v112, v174
	v_cndmask_b32_e64 v3, v3, v2, s[0:1]
	v_fmac_f32_e32 v175, v2, v113
	v_cndmask_b32_e64 v174, v3, v175, s[2:3]
	ds_read2st64_b32 v[2:3], v0 offset0:2 offset1:3
	ds_read2st64_b32 v[112:113], v0 offset0:10 offset1:11
	s_waitcnt lgkmcnt(0)
	v_fma_f32 v2, v175, v2, v112
	v_cndmask_b32_e64 v112, v174, v2, s[4:5]
	v_fmac_f32_e32 v113, v2, v3
	ds_read2st64_b32 v[2:3], v0 offset0:4 offset1:5
	ds_read2st64_b32 v[174:175], v0 offset0:12 offset1:13
	v_cndmask_b32_e64 v112, v112, v113, s[8:9]
	s_waitcnt lgkmcnt(0)
	v_fma_f32 v2, v113, v2, v174
	v_cndmask_b32_e64 v112, v112, v2, s[10:11]
	v_fmac_f32_e32 v175, v2, v3
	v_cndmask_b32_e64 v174, v112, v175, s[12:13]
	ds_read2st64_b32 v[112:113], v0 offset0:6 offset1:7
	ds_read2st64_b32 v[2:3], v0 offset0:14 offset1:15
	s_waitcnt lgkmcnt(0)
	v_fma_f32 v0, v175, v112, v2
	v_cndmask_b32_e64 v2, v174, v0, s[14:15]
	v_fma_f32 v2, v88, v2, v90
	v_fmac_f32_e32 v91, v89, v2
	ds_write2st64_b32 v176, v2, v91 offset0:42 offset1:43
	v_fma_f32 v2, v94, v91, v92
	v_fmac_f32_e32 v93, v95, v2
	ds_write2st64_b32 v176, v2, v93 offset0:44 offset1:45
	v_fma_f32 v2, v98, v93, v96
	v_fmac_f32_e32 v97, v99, v2
	ds_write2st64_b32 v176, v2, v97 offset0:46 offset1:47
	v_fma_f32 v2, v100, v97, v102
	v_fmac_f32_e32 v103, v101, v2
	ds_write2st64_b32 v176, v2, v103 offset0:48 offset1:49
	v_fma_f32 v2, v104, v103, v106
	v_fmac_f32_e32 v107, v105, v2
	ds_write2st64_b32 v176, v2, v107 offset0:50 offset1:51
	v_fma_f32 v2, v110, v107, v108
	v_fmac_f32_e32 v109, v111, v2
	ds_write2st64_b32 v176, v2, v109 offset0:52 offset1:53
	v_fma_f32 v2, v114, v109, v168
	v_fmac_f32_e32 v169, v115, v2
	ds_write2st64_b32 v176, v2, v169 offset0:54 offset1:55
	v_fma_f32 v2, v170, v169, v172
	v_fmac_f32_e32 v173, v171, v2
	ds_write2st64_b32 v176, v2, v173 offset0:56 offset1:57
	s_waitcnt lgkmcnt(0)
	v_add_u32_e32 v2, s19, v158
	v_cmp_gt_i32_e64 s[16:17], s86, v2
	s_waitcnt vmcnt(0)
	s_and_saveexec_b64 s[76:77], s[16:17]
	s_cbranch_execz .LBB0_595
	ds_read_b128 v[88:91], v125 offset:10880
	ds_read_b128 v[92:95], v125 offset:10896
	ds_read_b128 v[96:99], v125 offset:10912
	ds_read_b128 v[100:103], v125 offset:10928
	s_waitcnt lgkmcnt(3)
	v_cvt_pk_bf16_f32 v88, v88, v89
	v_cvt_pk_bf16_f32 v89, v90, v91
	s_waitcnt lgkmcnt(2)
	v_cvt_pk_bf16_f32 v90, v92, v93
	v_cvt_pk_bf16_f32 v91, v94, v95
	s_waitcnt lgkmcnt(1)
	v_cvt_pk_bf16_f32 v92, v96, v97
	v_cvt_pk_bf16_f32 v93, v98, v99
	s_waitcnt lgkmcnt(0)
	v_cvt_pk_bf16_f32 v94, v100, v101
	v_cvt_pk_bf16_f32 v95, v102, v103
	global_store_dwordx4 v[118:119], v[88:91], off
	global_store_dwordx4 v[118:119], v[92:95], off offset:16
	s_branch .LBB0_595
